# v21 plus next-tile DMA source-address VALU hoisted in front of the per-tile barrier (only M0 writes and global_load_lds remain after it)
# baseline (speedup 1.0000x reference)
; #define FA_SBAR() __builtin_amdgcn_sched_barrier(0)
; #define FA_WRITET(bf) do { *(LAS half8*)(lds + OFF_K + (bf) * SHM_K + kws) = st_k0; *(LAS half8*)(lds + OFF_K + (bf) * SHM_K + kws + 32 * 256) = st_k1; \
;         *(LAS half8*)(lds + OFF_V + (bf) * SHM_V + vst0) = st_v0; *(LAS half8*)(lds + OFF_V + (bf) * SHM_V + vst1) = st_v1; \
;         if constexpr (MLA) *(LAS half8*)(lds + OFF_KR + (bf) * SHM_KR + krw) = st_kr; } while (0)
; template <int KIND>
; __device__ __forceinline__ void run_unit(LAS char* lds, const UnitArgs& U, int tid_in) {
;     ...
;     for (int t = 0; t < NT; ++t) {
;         if (t + 1 < NT) FA_LOADT(U.j_lo + t + 1);
;         FA_SBAR();
;         FA_STEP(t);
;         FA_SBAR();
;         if (t + 1 < NT) { asm volatile("s_waitcnt vmcnt(0)" ::: "memory"); FA_WRITET((t + 1) & 1); dm_lo = dn_lo; dm_hi = dn_hi; }
;         __syncthreads();
.Ldsa_rot:
	s_cmp_lt_u32 s24, s15
	s_cselect_b64 s[6:7], -1, 0
	s_and_b32 s8, s24, 1
	v_mov_b32_e32 v2, s8
	s_cmp_gt_i32 s22, s17
	s_cselect_b64 vcc, -1, 0
	v_lshlrev_b32_e32 v2, 14, v2
	v_add_u32_e32 v6, v180, v2
	v_add_u32_e32 v196, v6, v181
	v_add_u32_e32 v197, v6, v182
	v_add_u32_e32 v208, v6, v183
	v_add_u32_e32 v209, v6, v184
	v_add_u32_e32 v114, s22, v162
	v_add_u32_e32 v116, 64, v114
	v_ashrrev_i32_e32 v117, 31, v116
	v_add_u32_e32 v118, 0x60, v114
	v_lshlrev_b64 v[116:117], 8, v[116:117]
	v_ashrrev_i32_e32 v119, 31, v118
	v_lshlrev_b64 v[118:119], 8, v[118:119]
	v_lshl_add_u64 v[120:121], v[166:167], 0, v[116:117]
	v_lshl_add_u64 v[122:123], v[166:167], 0, v[118:119]
	v_lshl_add_u64 v[124:125], v[168:169], 0, v[116:117]
	v_lshl_add_u64 v[126:127], v[168:169], 0, v[118:119]
	s_cmp_eq_u32 s13, s24
	s_waitcnt lgkmcnt(0)
	s_barrier
	s_cbranch_scc1 .LBB0_4942
	s_cbranch_vccnz .Ldsa_skipq
	ds_read_b128 v[6:9], v196 offset:32768
	ds_read_b128 v[10:13], v196 offset:40960
	ds_read_b128 v[14:17], v197 offset:32768
	ds_read_b128 v[188:191], v197 offset:40960
	ds_read_b128 v[192:195], v208 offset:32768
	ds_read_b128 v[204:207], v208 offset:40960
	ds_read_b128 v[220:223], v209 offset:32768
	ds_read_b128 v[224:227], v209 offset:40960
	s_and_b64 vcc, exec, s[6:7]
	s_cbranch_vccz .Ldsa_q_nold
	v_readfirstlane_b32 vcc_hi, v0
	s_and_b32 vcc_lo, s23, 0x4000
	s_lshr_b32 vcc_hi, vcc_hi, 6
	s_lshl_b32 vcc_hi, vcc_hi, 10
	s_add_i32 vcc_lo, vcc_lo, vcc_hi
	s_add_i32 m0, vcc_lo, 0x8000
	s_nop 0
	global_load_lds_dwordx4 v[120:121], off
	s_add_i32 m0, vcc_lo, 0xa000
	s_nop 0
	global_load_lds_dwordx4 v[122:123], off
	s_mov_b32 m0, vcc_lo
	s_nop 0
	global_load_lds_dwordx4 v[124:125], off
	s_add_i32 m0, vcc_lo, 0x2000
	s_nop 0
	global_load_lds_dwordx4 v[126:127], off
	s_nop 0
	global_load_dwordx2 v[4:5], v[170:171], off

; #define FA_SBAR() __builtin_amdgcn_sched_barrier(0)
; #define FA_WRITET(bf) do { *(LAS half8*)(lds + OFF_K + (bf) * SHM_K + kws) = st_k0; *(LAS half8*)(lds + OFF_K + (bf) * SHM_K + kws + 32 * 256) = st_k1; \
;         *(LAS half8*)(lds + OFF_V + (bf) * SHM_V + vst0) = st_v0; *(LAS half8*)(lds + OFF_V + (bf) * SHM_V + vst1) = st_v1; \
;         if constexpr (MLA) *(LAS half8*)(lds + OFF_KR + (bf) * SHM_KR + krw) = st_kr; } while (0)
; template <int KIND>
; __device__ __forceinline__ void run_unit(LAS char* lds, const UnitArgs& U, int tid_in) {
;     ...
;     for (int t = 0; t < NT; ++t) {
;         if (t + 1 < NT) FA_LOADT(U.j_lo + t + 1);
;         FA_SBAR();
;         FA_STEP(t);
;         FA_SBAR();
;         if (t + 1 < NT) { asm volatile("s_waitcnt vmcnt(0)" ::: "memory"); FA_WRITET((t + 1) & 1); dm_lo = dn_lo; dm_hi = dn_hi; }
;         __syncthreads();
.Lmoba_rot:
	s_cmp_lt_u32 s23, s15
	s_cselect_b64 s[6:7], -1, 0
	s_sub_i32 s8, s22, 63
	s_and_b32 s9, s23, 1
	v_mov_b32_e32 v2, s9
	s_cmp_gt_i32 s8, s24
	s_cselect_b64 vcc, -1, 0
	v_lshlrev_b32_e32 v2, 14, v2
	v_add_u32_e32 v4, v229, v2
	v_add_u32_e32 v16, v4, v230
	v_add_u32_e32 v17, v4, v231
	v_add_u32_e32 v102, v4, v232
	v_add_u32_e32 v103, v4, v233
	v_add_u32_e32 v146, s22, v204
	v_add_u32_e32 v148, 1, v146
	v_ashrrev_i32_e32 v149, 31, v148
	v_add_u32_e32 v150, 33, v146
	v_lshlrev_b64 v[148:149], 8, v[148:149]
	v_ashrrev_i32_e32 v151, 31, v150
	v_lshlrev_b64 v[150:151], 8, v[150:151]
	v_lshl_add_u64 v[152:153], v[206:207], 0, v[148:149]
	v_lshl_add_u64 v[154:155], v[206:207], 0, v[150:151]
	v_lshl_add_u64 v[156:157], v[208:209], 0, v[148:149]
	v_lshl_add_u64 v[158:159], v[208:209], 0, v[150:151]
	s_cmp_eq_u32 s13, s23
	s_waitcnt lgkmcnt(0)
	s_barrier
	s_cbranch_scc1 .LBB0_4964
	s_cbranch_vccnz .Lmoba_skipq
	ds_read_b128 v[4:7], v16 offset:32768
	ds_read_b128 v[8:11], v16 offset:40960
	ds_read_b128 v[12:15], v17 offset:32768
	ds_read_b128 v[82:85], v17 offset:40960
	ds_read_b128 v[86:89], v102 offset:32768
	ds_read_b128 v[90:93], v102 offset:40960
	ds_read_b128 v[94:97], v103 offset:32768
	ds_read_b128 v[98:101], v103 offset:40960
	s_and_b64 vcc, exec, s[6:7]
	s_cbranch_vccz .Lmoba_q_nold
	v_readfirstlane_b32 vcc_hi, v0
	s_and_b32 vcc_lo, s37, 0x4000
	s_lshr_b32 vcc_hi, vcc_hi, 6
	s_lshl_b32 vcc_hi, vcc_hi, 10
	s_add_i32 vcc_lo, vcc_lo, vcc_hi
	s_add_i32 m0, vcc_lo, 0x8000
	s_nop 0
	global_load_lds_dwordx4 v[152:153], off
	s_add_i32 m0, vcc_lo, 0xa000
	s_nop 0
	global_load_lds_dwordx4 v[154:155], off
	s_mov_b32 m0, vcc_lo
	s_nop 0
	global_load_lds_dwordx4 v[156:157], off
	s_add_i32 m0, vcc_lo, 0x2000
	s_nop 0
	global_load_lds_dwordx4 v[158:159], off

; #define FA_SBAR() __builtin_amdgcn_sched_barrier(0)
; #define FA_WRITET(bf) do { *(LAS half8*)(lds + OFF_K + (bf) * SHM_K + kws) = st_k0; *(LAS half8*)(lds + OFF_K + (bf) * SHM_K + kws + 32 * 256) = st_k1; \
;         *(LAS half8*)(lds + OFF_V + (bf) * SHM_V + vst0) = st_v0; *(LAS half8*)(lds + OFF_V + (bf) * SHM_V + vst1) = st_v1; \
;         if constexpr (MLA) *(LAS half8*)(lds + OFF_KR + (bf) * SHM_KR + krw) = st_kr; } while (0)
; template <int KIND>
; __device__ __forceinline__ void run_unit(LAS char* lds, const UnitArgs& U, int tid_in) {
;     ...
;     for (int t = 0; t < NT; ++t) {
;         if (t + 1 < NT) FA_LOADT(U.j_lo + t + 1);
;         FA_SBAR();
;         FA_STEP(t);
;         FA_SBAR();
;         if (t + 1 < NT) { asm volatile("s_waitcnt vmcnt(0)" ::: "memory"); FA_WRITET((t + 1) & 1); dm_lo = dn_lo; dm_hi = dn_hi; }
;         __syncthreads();
.Lmla_rot:
	s_cmp_lt_u32 s23, s15
	s_cselect_b64 s[6:7], -1, 0
	s_and_b32 s8, s23, 1
	v_mov_b32_e32 v4, s8
	s_cmp_gt_i32 s22, s17
	s_cselect_b64 vcc, -1, 0
	v_lshlrev_b32_e32 v2, 14, v4
	v_add_u32_e32 v5, v209, v2
	v_add_u32_e32 v214, v5, v220
	v_add_u32_e32 v248, v5, v221
	v_add_u32_e32 v249, v5, v222
	v_add_u32_e32 v5, v5, v223
	v_add_u32_e32 v114, s22, v182
	v_add_u32_e32 v116, 64, v114
	v_ashrrev_i32_e32 v117, 31, v116
	v_add_u32_e32 v118, 0x60, v114
	v_lshlrev_b64 v[116:117], 8, v[116:117]
	v_ashrrev_i32_e32 v119, 31, v118
	v_lshlrev_b64 v[118:119], 8, v[118:119]
	v_lshl_add_u64 v[120:121], v[184:185], 0, v[116:117]
	v_lshl_add_u64 v[122:123], v[184:185], 0, v[118:119]
	v_lshl_add_u64 v[124:125], v[186:187], 0, v[116:117]
	v_lshl_add_u64 v[126:127], v[186:187], 0, v[118:119]
	v_add_u32_e32 v128, s22, v227
	v_ashrrev_i32_e32 v129, 31, v128
	v_lshlrev_b64 v[128:129], 7, v[128:129]
	v_lshl_add_u64 v[178:179], v[188:189], 0, v[128:129]
	s_cmp_eq_u32 s13, s23
	s_waitcnt lgkmcnt(0)
	s_barrier
	s_cbranch_scc1 .LBB0_4984
	s_cbranch_vccnz .Lmla_skipq
	ds_read_b128 v[6:9], v214 offset:32768
	ds_read_b128 v[10:13], v214 offset:40960
	ds_read_b128 v[14:17], v248 offset:32768
	ds_read_b128 v[230:233], v248 offset:40960
	ds_read_b128 v[234:237], v249 offset:32768
	ds_read_b128 v[240:243], v249 offset:40960
	ds_read_b128 v[244:247], v5 offset:32768
	ds_read_b128 v[194:197], v5 offset:40960
	s_and_b64 vcc, exec, s[6:7]
	s_cbranch_vccz .Lmla_q_nold
	v_readfirstlane_b32 s9, v0
	s_add_i32 s8, s23, 1
	s_and_b32 s8, s8, 1
	s_lshr_b32 s9, s9, 6
	s_lshl_b32 s9, s9, 10
	s_lshl_b32 vcc_lo, s8, 14
	s_add_i32 vcc_lo, vcc_lo, s9
	s_lshl_b32 s8, s8, 13
	s_add_i32 s8, s8, s9
	s_add_i32 s8, s8, 0x10000
	s_add_i32 m0, vcc_lo, 0x8000
	s_nop 0
	global_load_lds_dwordx4 v[120:121], off
	s_add_i32 m0, vcc_lo, 0xa000
	s_nop 0
	global_load_lds_dwordx4 v[122:123], off
	s_mov_b32 m0, vcc_lo
	s_nop 0
	global_load_lds_dwordx4 v[124:125], off
	s_add_i32 m0, vcc_lo, 0x2000
	s_nop 0
	global_load_lds_dwordx4 v[126:127], off
	s_mov_b32 m0, s8
	s_nop 0
	global_load_lds_dwordx4 v[178:179], off

; #define FA_SBAR() __builtin_amdgcn_sched_barrier(0)
; #define FA_WRITET(bf) do { *(LAS half8*)(lds + OFF_K + (bf) * SHM_K + kws) = st_k0; *(LAS half8*)(lds + OFF_K + (bf) * SHM_K + kws + 32 * 256) = st_k1; \
;         *(LAS half8*)(lds + OFF_V + (bf) * SHM_V + vst0) = st_v0; *(LAS half8*)(lds + OFF_V + (bf) * SHM_V + vst1) = st_v1; \
;         if constexpr (MLA) *(LAS half8*)(lds + OFF_KR + (bf) * SHM_KR + krw) = st_kr; } while (0)
; template <int KIND>
; __device__ __forceinline__ void run_unit(LAS char* lds, const UnitArgs& U, int tid_in) {
;     ...
;     for (int t = 0; t < NT; ++t) {
;         if (t + 1 < NT) FA_LOADT(U.j_lo + t + 1);
;         FA_SBAR();
;         FA_STEP(t);
;         FA_SBAR();
;         if (t + 1 < NT) { asm volatile("s_waitcnt vmcnt(0)" ::: "memory"); FA_WRITET((t + 1) & 1); dm_lo = dn_lo; dm_hi = dn_hi; }
;         __syncthreads();
.Lslc_rot:
	s_cmp_lt_u32 s25, s15
	s_cselect_b64 s[6:7], -1, 0
	s_sub_i32 s10, s22, 63
	s_and_b32 s11, s25, 1
	v_mov_b32_e32 v2, s11
	s_cmp_gt_i32 s10, s24
	s_cselect_b64 vcc, -1, 0
	v_lshlrev_b32_e32 v2, 14, v2
	v_add_u32_e32 v4, v182, v2
	v_add_u32_e32 v16, v4, v183
	v_add_u32_e32 v17, v4, v184
	v_add_u32_e32 v191, v4, v185
	v_add_u32_e32 v196, v4, v186
	v_add_u32_e32 v114, s22, v166
	v_add_u32_e32 v116, 1, v114
	v_ashrrev_i32_e32 v117, 31, v116
	v_add_u32_e32 v118, 33, v114
	v_lshlrev_b64 v[116:117], 8, v[116:117]
	v_ashrrev_i32_e32 v119, 31, v118
	v_lshlrev_b64 v[118:119], 8, v[118:119]
	v_lshl_add_u64 v[120:121], v[170:171], 0, v[116:117]
	v_lshl_add_u64 v[122:123], v[170:171], 0, v[118:119]
	v_lshl_add_u64 v[124:125], v[172:173], 0, v[116:117]
	v_lshl_add_u64 v[126:127], v[172:173], 0, v[118:119]
	s_cmp_eq_u32 s13, s25
	s_waitcnt lgkmcnt(0)
	s_barrier
	s_cbranch_scc1 .LBB0_5002
	s_cbranch_vccnz .Lslc_skipq
	ds_read_b128 v[4:7], v16 offset:32768
	ds_read_b128 v[8:11], v16 offset:40960
	ds_read_b128 v[12:15], v17 offset:32768
	ds_read_b128 v[192:195], v17 offset:40960
	ds_read_b128 v[204:207], v191 offset:32768
	ds_read_b128 v[220:223], v191 offset:40960
	ds_read_b128 v[224:227], v196 offset:32768
	ds_read_b128 v[228:231], v196 offset:40960
	s_and_b64 vcc, exec, s[6:7]
	s_cbranch_vccz .Lslc_q_nold
	v_readfirstlane_b32 vcc_hi, v0
	s_and_b32 vcc_lo, s37, 0x4000
	s_lshr_b32 vcc_hi, vcc_hi, 6
	s_lshl_b32 vcc_hi, vcc_hi, 10
	s_add_i32 vcc_lo, vcc_lo, vcc_hi
	s_add_i32 m0, vcc_lo, 0x8000
	s_nop 0
	global_load_lds_dwordx4 v[120:121], off
	s_add_i32 m0, vcc_lo, 0xa000
	s_nop 0
	global_load_lds_dwordx4 v[122:123], off
	s_mov_b32 m0, vcc_lo
	s_nop 0
	global_load_lds_dwordx4 v[124:125], off
	s_add_i32 m0, vcc_lo, 0x2000
	s_nop 0
	global_load_lds_dwordx4 v[126:127], off
